# v20 + ssm_fused Sl rows padded 512->528 B (8-way ds_write_b128 bank conflict), scan reads as ds_read_b32 with byte offsets
# speedup vs baseline: 1.0005x; 1.0005x over previous
.LBB0_100:
	s_andn2_b64 vcc, exec, s[2:3]
	s_cbranch_vccnz .LBB0_195
	s_mov_b32 s2, s87
	s_ashr_i32 s3, s2, 31
	v_readlane_b32 s4, v251, 4
	v_readlane_b32 s5, v251, 5
	s_add_u32 s12, s4, s2
	s_addc_u32 s13, s5, s3
	s_lshl_b64 s[4:5], s[2:3], 3
	v_readlane_b32 s6, v251, 0
	v_readlane_b32 s7, v251, 1
	s_add_u32 s76, s6, s4
	s_addc_u32 s77, s7, s5
	s_andn2_b64 vcc, exec, s[54:55]
	s_mov_b64 s[4:5], -1
	s_cbranch_vccnz .LBB0_128
	v_readlane_b32 s4, v251, 15
	v_readlane_b32 s5, v251, 16
	v_mov_b32_e32 v0, v176
	s_andn2_b64 vcc, exec, s[4:5]
	s_cbranch_vccnz .LBB0_127
	s_lshl_b64 s[4:5], s[50:51], 15
	s_ashr_i32 s57, s56, 31
	s_add_u32 s16, s12, 0xbe00000
	s_addc_u32 s17, s13, 0
	s_add_u32 s18, s12, 0x600000
	s_addc_u32 s19, s13, 0
	s_add_u32 s21, s12, 0xa00000
	s_addc_u32 s25, s13, 0
	s_load_dwordx2 s[6:7], s[76:77], 0x58
	s_add_u32 s4, s12, s4
	s_addc_u32 s5, s13, s5
	s_add_u32 s48, s4, 0x2a00000
	s_addc_u32 s49, s5, 0
	s_lshl_b64 s[4:5], s[56:57], 2
	s_waitcnt lgkmcnt(0)
	s_add_u32 s40, s6, s4
	s_addc_u32 s41, s7, s5
	s_add_u32 s51, s12, 0x15e00000
	s_movk_i32 s4, 0x7f
	s_addc_u32 s57, s13, 0
	v_ashrrev_i32_e32 v4, 6, v0
	v_cmp_lt_i32_e64 s[44:45], s4, v0
	v_readlane_b32 s4, v251, 4
	v_and_b32_e32 v2, 63, v0
	v_and_b32_e32 v5, 3, v4
	v_readlane_b32 s5, v251, 5
	s_add_u32 s4, s4, s2
	v_lshlrev_b32_e32 v134, 1, v2
	v_lshlrev_b32_e32 v157, 2, v5
	v_mov_b32_e32 v135, v1
	s_addc_u32 s5, s5, s3
	v_lshlrev_b32_e32 v3, 2, v2
	v_ashrrev_i32_e32 v6, 8, v0
	v_bfe_u32 v152, v0, 4, 2
	v_and_b32_e32 v153, 15, v0
	v_mul_u32_u24_e32 v0, 0x10800, v4
	v_or_b32_e32 v158, 1, v157
	v_or_b32_e32 v159, 2, v157
	v_or_b32_e32 v160, 3, v157
	v_lshl_add_u64 v[136:137], s[4:5], 0, v[134:135]
	v_readlane_b32 s4, v250, 43
	v_lshlrev_b32_e32 v7, 8, v5
	v_lshlrev_b32_e32 v154, 7, v4
	v_add3_u32 v155, 0, v3, v0
	v_lshlrev_b32_e32 v156, 7, v6
	v_mul_u32_u24_e32 v3, 0x10800, v6
	v_lshlrev_b32_e32 v0, 6, v5
	v_lshlrev_b32_e32 v2, 4, v158
	v_lshlrev_b32_e32 v4, 4, v159
	v_lshlrev_b32_e32 v6, 4, v160
	s_add_u32 s62, s4, s2
	v_readlane_b32 s2, v250, 44
	v_cmp_gt_u32_e64 s[42:43], 2, v5
	v_add3_u32 v161, 0, v7, v3
	s_addc_u32 s63, s2, s3
	v_lshlrev_b32_e32 v0, 1, v0
	v_lshlrev_b32_e32 v138, 1, v2
	v_lshlrev_b32_e32 v140, 1, v4
	v_lshlrev_b32_e32 v142, 1, v6
	s_mov_b32 s65, s14
	s_branch .LBB0_105

.LBB0_111:
	v_mov_b32_e32 v130, v152
	v_mov_b32_e32 v131, v153
	s_and_saveexec_b64 s[6:7], s[42:43]
	s_cbranch_execz .LBB0_113
	v_lshlrev_b32_e32 v130, 4, v130
	v_mul_u32_u24_e32 v131, 0x210, v131
	v_add3_u32 v130, v161, v130, v131
	ds_write_b128 v130, v[126:129]
	ds_write_b128 v130, v[122:125] offset:64
	ds_write_b128 v130, v[118:121] offset:128
	ds_write_b128 v130, v[114:117] offset:192
	ds_write_b128 v130, v[110:113] offset:8448
	ds_write_b128 v130, v[106:109] offset:8512
	ds_write_b128 v130, v[102:105] offset:8576
	ds_write_b128 v130, v[98:101] offset:8640
	ds_write_b128 v130, v[94:97] offset:16896
	ds_write_b128 v130, v[90:93] offset:16960
	ds_write_b128 v130, v[86:89] offset:17024
	ds_write_b128 v130, v[82:85] offset:17088
	ds_write_b128 v130, v[78:81] offset:25344
	ds_write_b128 v130, v[74:77] offset:25408
	ds_write_b128 v130, v[70:73] offset:25472
	ds_write_b128 v130, v[66:69] offset:25536
	ds_write_b128 v130, v[62:65] offset:33792
	ds_write_b128 v130, v[58:61] offset:33856
	ds_write_b128 v130, v[54:57] offset:33920
	ds_write_b128 v130, v[50:53] offset:33984
	ds_write_b128 v130, v[46:49] offset:42240
	ds_write_b128 v130, v[42:45] offset:42304
	ds_write_b128 v130, v[38:41] offset:42368
	ds_write_b128 v130, v[34:37] offset:42432
	ds_write_b128 v130, v[30:33] offset:50688
	ds_write_b128 v130, v[26:29] offset:50752
	ds_write_b128 v130, v[22:25] offset:50816
	ds_write_b128 v130, v[18:21] offset:50880
	ds_write_b128 v130, v[14:17] offset:59136
	ds_write_b128 v130, v[10:13] offset:59200
	ds_write_b128 v130, v[6:9] offset:59264
	ds_write_b128 v130, v[2:5] offset:59328

.LBB0_117:
	ds_read_b32 v20, v12
	ds_read_b32 v21, v12 offset:256
	ds_read_b32 v22, v12 offset:528
	ds_read_b32 v23, v12 offset:784
	ds_read_b32 v24, v12 offset:1056
	ds_read_b32 v25, v12 offset:1312
	ds_read_b32 v26, v12 offset:1584
	ds_read_b32 v27, v12 offset:1840
	ds_read_b32 v28, v12 offset:2112
	ds_read_b32 v29, v12 offset:2368
	ds_read_b32 v30, v12 offset:2640
	ds_read_b32 v31, v12 offset:2896
	ds_read_b32 v32, v12 offset:3168
	ds_read_b32 v33, v12 offset:3424
	v_bfe_u32 v10, v8, 16, 1
	v_add3_u32 v13, v8, v10, s36
	v_lshl_add_u64 v[10:11], v[4:5], 0, s[10:11]
	v_add_co_u32_e32 v14, vcc, 0x13e00000, v10
	v_pk_mul_f32 v[16:17], v[6:7], v[8:9] op_sel:[0,1]
	s_nop 0
	v_addc_co_u32_e32 v15, vcc, 0, v11, vcc
	global_store_short_d16_hi v[14:15], v13, off
	v_bfe_u32 v13, v9, 16, 1
	v_add3_u32 v13, v9, v13, s36
	global_store_short_d16_hi v[14:15], v13, off offset:128
	v_pk_fma_f32 v[18:19], v[2:3], v[8:9], v[16:17] neg_lo:[0,0,1] neg_hi:[0,0,1]
	v_pk_fma_f32 v[8:9], v[2:3], v[8:9], v[16:17] op_sel_hi:[1,0,1]
	s_mov_b32 s5, 0x13e08000
	v_mov_b32_e32 v19, v9
	s_waitcnt lgkmcnt(12)
	ds_read_b32 v34, v12 offset:3696
	ds_read_b32 v35, v12 offset:3952
	v_pk_add_f32 v[8:9], v[18:19], v[20:21]
	v_add_co_u32_e32 v14, vcc, s37, v10
	v_bfe_u32 v13, v8, 16, 1
	v_add3_u32 v13, v8, v13, s36
	v_addc_co_u32_e32 v15, vcc, 0, v11, vcc
	global_store_short_d16_hi v[14:15], v13, off
	v_bfe_u32 v13, v9, 16, 1
	v_add3_u32 v13, v9, v13, s36
	global_store_short_d16_hi v[14:15], v13, off offset:128
	v_pk_mul_f32 v[16:17], v[6:7], v[8:9] op_sel:[0,1]
	s_add_u32 s10, s10, 0x20000
	v_pk_fma_f32 v[18:19], v[2:3], v[8:9], v[16:17] neg_lo:[0,0,1] neg_hi:[0,0,1]
	v_pk_fma_f32 v[8:9], v[2:3], v[8:9], v[16:17] op_sel_hi:[1,0,1]
	s_addc_u32 s11, s11, 0
	v_mov_b32_e32 v19, v9
	s_waitcnt lgkmcnt(12)
	v_pk_add_f32 v[8:9], v[18:19], v[22:23]
	v_add_co_u32_e32 v14, vcc, s5, v10
	v_bfe_u32 v13, v8, 16, 1
	v_add3_u32 v13, v8, v13, s36
	v_addc_co_u32_e32 v15, vcc, 0, v11, vcc
	global_store_short_d16_hi v[14:15], v13, off
	v_bfe_u32 v13, v9, 16, 1
	v_add3_u32 v13, v9, v13, s36
	global_store_short_d16_hi v[14:15], v13, off offset:128
	v_pk_mul_f32 v[16:17], v[6:7], v[8:9] op_sel:[0,1]
	s_mov_b32 s5, 0x13e0c000
	v_pk_fma_f32 v[18:19], v[2:3], v[8:9], v[16:17] neg_lo:[0,0,1] neg_hi:[0,0,1]
	v_pk_fma_f32 v[8:9], v[2:3], v[8:9], v[16:17] op_sel_hi:[1,0,1]
	s_cmp_lg_u32 s10, 0x200000
	v_mov_b32_e32 v19, v9
	s_waitcnt lgkmcnt(10)
	v_pk_add_f32 v[8:9], v[18:19], v[24:25]
	v_add_co_u32_e32 v14, vcc, s5, v10
	v_bfe_u32 v13, v8, 16, 1
	v_add3_u32 v13, v8, v13, s36
	v_addc_co_u32_e32 v15, vcc, 0, v11, vcc
	global_store_short_d16_hi v[14:15], v13, off
	v_bfe_u32 v13, v9, 16, 1
	v_add3_u32 v13, v9, v13, s36
	global_store_short_d16_hi v[14:15], v13, off offset:128
	v_pk_mul_f32 v[16:17], v[6:7], v[8:9] op_sel:[0,1]
	s_mov_b32 s5, 0x13e10000
	v_pk_fma_f32 v[18:19], v[2:3], v[8:9], v[16:17] neg_lo:[0,0,1] neg_hi:[0,0,1]
	v_pk_fma_f32 v[8:9], v[2:3], v[8:9], v[16:17] op_sel_hi:[1,0,1]
	s_nop 0
	v_mov_b32_e32 v19, v9
	s_waitcnt lgkmcnt(8)
	v_pk_add_f32 v[8:9], v[18:19], v[26:27]
	v_add_co_u32_e32 v14, vcc, s5, v10
	v_bfe_u32 v13, v8, 16, 1
	v_add3_u32 v13, v8, v13, s36
	v_addc_co_u32_e32 v15, vcc, 0, v11, vcc
	global_store_short_d16_hi v[14:15], v13, off
	v_bfe_u32 v13, v9, 16, 1
	v_add3_u32 v13, v9, v13, s36
	global_store_short_d16_hi v[14:15], v13, off offset:128
	v_pk_mul_f32 v[16:17], v[6:7], v[8:9] op_sel:[0,1]
	s_mov_b32 s5, 0x13e14000
	v_pk_fma_f32 v[18:19], v[2:3], v[8:9], v[16:17] neg_lo:[0,0,1] neg_hi:[0,0,1]
	v_pk_fma_f32 v[8:9], v[2:3], v[8:9], v[16:17] op_sel_hi:[1,0,1]
	s_nop 0
	v_mov_b32_e32 v19, v9
	s_waitcnt lgkmcnt(6)
	v_pk_add_f32 v[8:9], v[18:19], v[28:29]
	v_add_co_u32_e32 v14, vcc, s5, v10
	v_bfe_u32 v13, v8, 16, 1
	v_add3_u32 v13, v8, v13, s36
	v_addc_co_u32_e32 v15, vcc, 0, v11, vcc
	global_store_short_d16_hi v[14:15], v13, off
	v_bfe_u32 v13, v9, 16, 1
	v_add3_u32 v13, v9, v13, s36
	global_store_short_d16_hi v[14:15], v13, off offset:128
	v_pk_mul_f32 v[16:17], v[6:7], v[8:9] op_sel:[0,1]
	s_mov_b32 s5, 0x13e18000
	v_pk_fma_f32 v[18:19], v[2:3], v[8:9], v[16:17] neg_lo:[0,0,1] neg_hi:[0,0,1]
	v_pk_fma_f32 v[8:9], v[2:3], v[8:9], v[16:17] op_sel_hi:[1,0,1]
	s_nop 0
	v_mov_b32_e32 v19, v9
	s_waitcnt lgkmcnt(4)
	v_pk_add_f32 v[8:9], v[18:19], v[30:31]
	v_add_co_u32_e32 v14, vcc, s5, v10
	v_bfe_u32 v13, v8, 16, 1
	v_add3_u32 v13, v8, v13, s36
	v_addc_co_u32_e32 v15, vcc, 0, v11, vcc
	global_store_short_d16_hi v[14:15], v13, off
	v_bfe_u32 v13, v9, 16, 1
	v_add3_u32 v13, v9, v13, s36
	global_store_short_d16_hi v[14:15], v13, off offset:128
	v_pk_mul_f32 v[16:17], v[6:7], v[8:9] op_sel:[0,1]
	s_mov_b32 s5, 0x13e1c000
	v_pk_fma_f32 v[18:19], v[2:3], v[8:9], v[16:17] neg_lo:[0,0,1] neg_hi:[0,0,1]
	v_pk_fma_f32 v[8:9], v[2:3], v[8:9], v[16:17] op_sel_hi:[1,0,1]
	v_add_co_u32_e32 v10, vcc, s5, v10
	v_mov_b32_e32 v19, v9
	s_waitcnt lgkmcnt(2)
	v_pk_add_f32 v[8:9], v[18:19], v[32:33]
	v_addc_co_u32_e32 v11, vcc, 0, v11, vcc
	v_bfe_u32 v13, v8, 16, 1
	v_add3_u32 v13, v8, v13, s36
	global_store_short_d16_hi v[10:11], v13, off
	v_bfe_u32 v13, v9, 16, 1
	v_add3_u32 v13, v9, v13, s36
	global_store_short_d16_hi v[10:11], v13, off offset:128
	v_pk_mul_f32 v[14:15], v[6:7], v[8:9] op_sel:[0,1]
	v_add_u32_e32 v12, 0x1080, v12
	v_pk_fma_f32 v[16:17], v[2:3], v[8:9], v[14:15] neg_lo:[0,0,1] neg_hi:[0,0,1]
	v_pk_fma_f32 v[8:9], v[2:3], v[8:9], v[14:15] op_sel_hi:[1,0,1]
	s_nop 0
	v_mov_b32_e32 v17, v9
	s_waitcnt lgkmcnt(0)
	v_pk_add_f32 v[8:9], v[16:17], v[34:35]
	s_cbranch_scc1 .LBB0_117
	v_mov_b64_e32 v[2:3], s[8:9]
